# v2 + pool loop counted vmcnt + NA K-fragment LDS address hoisted out of item loop
# speedup vs baseline: 1.0389x; 1.0013x over previous
.LBB0_577:
	v_ashrrev_i32_e32 v6, 3, v94
	v_add_u32_e32 v3, 0xffffc000, v6
	v_and_b32_e32 v0, -4, v6
	v_lshrrev_b32_e32 v3, 14, v3
	s_movk_i32 s0, 0x4000
	v_ashrrev_i32_e32 v2, 14, v94
	v_add_u32_e32 v3, 8, v3
	v_cmp_gt_i32_e32 vcc, s0, v0
	v_mov_b32_e32 v4, 0xfffe4000
	v_mov_b32_e32 v5, 0x800
	v_cndmask_b32_e32 v2, v3, v2, vcc
	v_lshlrev_b32_e32 v3, 11, v2
	v_lshl_add_u32 v4, v2, 14, v4
	v_cmp_gt_i32_e32 vcc, 8, v2
	v_mov_b32_e32 v2, 0x4000
	s_waitcnt vmcnt(4)
	v_mov_b32_e32 v74, 0
	v_cndmask_b32_e32 v2, v2, v5, vcc
	v_cndmask_b32_e32 v129, v4, v3, vcc
	v_add_u32_e32 v128, v129, v2
	v_add_u32_e32 v2, -8, v0
	v_cmp_ge_i32_e32 vcc, v2, v129
	s_and_b64 s[0:1], s[38:39], vcc
	v_cmp_lt_i32_e32 vcc, v2, v128
	s_and_b64 s[0:1], s[0:1], vcc
	v_mov_b32_e32 v78, 0
	v_mov_b32_e32 v79, 0
	v_mov_b32_e32 v80, 0
	v_mov_b32_e32 v81, 0
	s_and_saveexec_b64 s[46:47], s[0:1]
	s_cbranch_execz .LBB0_579
	v_mad_i64_i32 v[2:3], s[0:1], v2, s9, v[96:97]
	global_load_dwordx4 v[78:81], v[2:3], off

.LBB0_703:
	v_sub_u32_e64 v0, s0, 4 clamp
	v_ashrrev_i32_e32 v57, 3, v152
	v_readfirstlane_b32 s0, v0
	v_sub_u32_e64 v0, v61, 8 clamp
	v_lshrrev_b32_e32 v5, 2, v57
	v_min_u32_e32 v2, 48, v0
	v_and_b32_e32 v3, 7, v152
	v_bfe_u32 v0, v57, 1, 1
	v_and_b32_e32 v5, 6, v5
	v_bitop3_b32 v0, v0, v3, v5 bitop3:0x36
	v_lshl_add_u32 v65, v0, 4, 0
	v_lshlrev_b32_e32 v0, 3, v152
	v_and_b32_e32 v64, 56, v0
	v_lshlrev_b32_e32 v0, 4, v152
	v_and_b32_e32 v0, 0x3f0, v0
	v_lshrrev_b32_e32 v5, 5, v152
	s_and_b64 s[38:39], s[40:41], exec
	v_lshl_add_u64 v[66:67], s[16:17], 0, v[0:1]
	v_bfe_u32 v0, v152, 4, 1
	v_and_b32_e32 v5, 6, v5
	s_cselect_b32 s1, 24, 0xf8
	v_bitop3_b32 v0, v0, v3, v5 bitop3:0x36
	s_min_u32 s66, s0, s1
	v_readlane_b32 s0, v255, 21
	v_lshl_add_u32 v83, v0, 4, 0
	v_lshlrev_b32_e32 v0, 1, v199
	v_add_u32_e32 v88, s82, v150
	v_lshl_add_u32 v4, v193, 2, s0
	s_add_i32 s10, 0, 0x12000
	s_add_i32 s20, s59, -1
	s_and_b32 s83, s25, 4
	v_and_b32_e32 v85, 24, v0
	s_and_b32 s0, s25, -4
	v_add_u32_e32 v0, 16, v2
	v_or_b32_e32 v120, 4, v88
	s_cmp_eq_u32 s0, 4
	v_cmp_ge_i32_e32 vcc, v120, v2
	v_cmp_lt_i32_e64 s[40:41], v120, v0
	s_cselect_b64 s[80:81], -1, 0
	s_and_b64 s[40:41], vcc, s[40:41]
	v_cmp_ge_i32_e32 vcc, v88, v2
	v_cmp_lt_i32_e64 s[42:43], v88, v0
	v_or_b32_e32 v121, 1, v88
	s_and_b64 s[42:43], vcc, s[42:43]
	v_cmp_ge_i32_e32 vcc, v121, v2
	v_cmp_lt_i32_e64 s[44:45], v121, v0
	v_or_b32_e32 v122, 2, v88
	s_and_b64 s[44:45], vcc, s[44:45]
	v_cmp_ge_i32_e32 vcc, v122, v2
	v_cmp_lt_i32_e64 s[46:47], v122, v0
	v_or_b32_e32 v123, 3, v88
	s_and_b64 s[46:47], vcc, s[46:47]
	v_cmp_ge_i32_e32 vcc, v123, v2
	v_cmp_lt_i32_e64 s[48:49], v123, v0
	v_or_b32_e32 v124, 5, v88
	s_and_b64 s[48:49], vcc, s[48:49]
	v_cmp_ge_i32_e32 vcc, v124, v2
	v_cmp_lt_i32_e64 s[50:51], v124, v0
	v_or_b32_e32 v125, 6, v88
	v_or_b32_e32 v126, 7, v88
	v_lshl_add_u32 v60, v3, 4, s10
	v_and_b32_e32 v3, -16, v193
	s_and_b64 s[50:51], vcc, s[50:51]
	v_cmp_ge_i32_e32 vcc, v125, v2
	v_cmp_lt_i32_e64 s[52:53], v125, v0
	v_cmp_lt_i32_e64 s[54:55], v126, v0
	v_mul_u32_u24_e32 v0, 0x410, v199
	s_movk_i32 s35, 0x410
	s_mul_i32 s26, s58, 0xa00
	v_add_u32_e32 v5, 0x200, v152
	v_add_u32_e32 v6, 0x400, v152
	v_add_u32_e32 v7, 0x600, v152
	v_add_u32_e32 v8, 0x800, v152
	v_add_u32_e32 v9, 0xa00, v152
	v_add_u32_e32 v10, 0xc00, v152
	v_add_u32_e32 v11, 0xe00, v152
	s_and_b64 s[52:53], vcc, s[52:53]
	v_cmp_ge_i32_e32 vcc, v126, v2
	v_add3_u32 v127, s10, v3, v0
	v_mov_b32_e32 v2, v1
	v_mov_b32_e32 v3, v1
	v_mad_u64_u32 v[62:63], s[38:39], v57, s35, v[60:61]
	v_ashrrev_i32_e32 v89, 6, v152
	v_ashrrev_i32_e32 v90, 3, v5
	v_ashrrev_i32_e32 v91, 6, v5
	v_ashrrev_i32_e32 v92, 3, v6
	v_ashrrev_i32_e32 v93, 6, v6
	v_ashrrev_i32_e32 v94, 3, v7
	v_ashrrev_i32_e32 v95, 6, v7
	v_ashrrev_i32_e32 v96, 3, v8
	v_ashrrev_i32_e32 v97, 6, v8
	v_ashrrev_i32_e32 v98, 3, v9
	v_ashrrev_i32_e32 v99, 6, v9
	v_ashrrev_i32_e32 v100, 3, v10
	v_ashrrev_i32_e32 v101, 6, v10
	v_ashrrev_i32_e32 v102, 3, v11
	v_ashrrev_i32_e32 v103, 6, v11
	v_lshrrev_b32_e32 v106, 9, v5
	v_lshrrev_b32_e32 v108, 9, v6
	v_lshrrev_b32_e32 v110, 9, v7
	v_lshrrev_b32_e32 v112, 9, v8
	v_lshrrev_b32_e32 v114, 9, v9
	v_lshrrev_b32_e32 v116, 9, v10
	v_lshrrev_b32_e32 v118, 9, v11
	v_mov_b32_e32 v0, v1
	v_add_u32_e32 v128, s26, v4
	v_mov_b64_e32 v[6:7], v[2:3]
	v_mov_b64_e32 v[10:11], v[2:3]
	s_mov_b32 s1, 2
	v_lshrrev_b32_e32 v63, 3, v152
	v_bfe_u32 v82, v152, 3, 6
	s_mov_b32 s38, -1
	v_add_u32_e32 v84, 0x200, v57
	v_and_b32_e32 v86, 3, v193
	v_add_u32_e32 v87, 4, v198
	v_lshrrev_b32_e32 v104, 9, v152
	v_mul_lo_u32 v105, v89, s35
	v_mul_lo_u32 v107, v91, s35
	v_mul_lo_u32 v109, v93, s35
	v_mul_lo_u32 v111, v95, s35
	v_mul_lo_u32 v113, v97, s35
	v_mul_lo_u32 v115, v99, s35
	v_mul_lo_u32 v117, v101, s35
	v_mul_lo_u32 v119, v103, s35
	s_and_b64 s[54:55], vcc, s[54:55]
	v_mov_b32_e32 v129, 0
	v_mov_b32_e32 v130, 0
	v_mov_b32_e32 v131, 0
	v_mov_b32_e32 v132, 0
	v_mov_b32_e32 v133, 0
	v_mov_b32_e32 v134, 0
	v_mov_b32_e32 v135, 0
	v_mov_b32_e32 v136, 0
	v_mov_b32_e32 v137, 0
	v_mov_b32_e32 v138, 0
	v_mov_b32_e32 v139, 0
	v_mov_b32_e32 v140, 0
	v_mov_b32_e32 v141, 0
	v_mov_b32_e32 v142, 0
	v_mov_b32_e32 v143, 0
	v_mov_b32_e32 v144, 0
	v_mov_b32_e32 v145, 0
	v_mov_b32_e32 v146, 0
	v_mov_b32_e32 v147, 0
	v_mov_b32_e32 v148, 0
	v_mov_b32_e32 v149, 0
	v_mov_b32_e32 v152, 0
	v_mov_b32_e32 v154, 0
	v_mov_b32_e32 v155, 0
	v_mov_b32_e32 v156, 0
	v_mov_b32_e32 v157, 0
	v_mov_b32_e32 v158, 0
	v_mov_b32_e32 v159, 0
	v_mov_b32_e32 v160, 0
	v_mov_b32_e32 v161, 0
	v_mov_b32_e32 v162, 0
	v_mov_b32_e32 v163, 0
	v_mov_b64_e32 v[4:5], v[0:1]
	v_mov_b64_e32 v[8:9], v[0:1]
	s_waitcnt vmcnt(0)
	v_add_u32_e32 v250, s82, v85
	v_or_b32_e32 v251, v250, v86
	v_lshrrev_b32_e32 v250, 2, v250
	v_lshlrev_b32_e32 v252, 7, v251
	v_bfe_u32 v251, v251, 1, 1
	v_and_b32_e32 v250, 6, v250
	v_bitop3_b32 v248, v251, v198, v250 bitop3:0x36
	v_bitop3_b32 v249, v251, v87, v250 bitop3:0x36
	v_lshl_add_u32 v248, v248, 4, v252
	v_lshl_add_u32 v249, v249, 4, v252
	s_branch .LBB0_705

.LBB0_716:
	s_add_i32 s10, s91, s83
	s_lshl_b32 s10, s10, 6
	s_and_b32 s26, s10, 0x1c0
	s_or_b32 vcc_hi, s26, s82
	s_lshl_b32 s26, s26, 7
	v_add_u32_e32 v250, s26, v248
	v_add_u32_e32 v251, s26, v249
	s_add_i32 s26, s10, 64
	s_and_b32 s26, s26, 0x1c0
	s_or_b32 s35, s26, s82
	ds_read_b128 v[28:31], v250
	ds_read_b128 v[32:35], v251
	ds_read_b128 v[36:39], v250 offset:512
	ds_read_b128 v[40:43], v251 offset:512
	s_lshl_b32 s26, s26, 7
	v_add_u32_e32 v252, s26, v248
	v_add_u32_e32 v253, s26, v249
	s_add_i32 s26, s10, 0x80
	s_and_b32 s26, s26, 0x1c0
	s_or_b32 vcc_lo, s26, s82
	ds_read_b128 v[44:47], v252
	ds_read_b128 v[164:167], v253
	ds_read_b128 v[168:171], v252 offset:512
	ds_read_b128 v[172:175], v253 offset:512
	s_lshl_b32 s26, s26, 7
	v_add_u32_e32 v250, s26, v248
	v_add_u32_e32 v251, s26, v249
	s_addk_i32 s10, 0xc0
	s_and_b32 s10, s10, 0x1c0
	ds_read_b128 v[176:179], v250
	ds_read_b128 v[180:183], v251
	ds_read_b128 v[200:203], v250 offset:512
	ds_read_b128 v[204:207], v251 offset:512
	s_lshl_b32 s26, s10, 7
	s_or_b32 s10, s10, s82
	v_add_u32_e32 v252, s26, v248
	v_add_u32_e32 v253, s26, v249
	ds_read_b128 v[208:211], v252
	ds_read_b128 v[212:215], v253
	ds_read_b128 v[216:219], v252 offset:512
	ds_read_b128 v[220:223], v253 offset:512
	s_setprio 1
	s_waitcnt lgkmcnt(14)
	v_mfma_f32_16x16x32_bf16 v[28:31], v[28:31], v[24:27], 0
	v_mfma_f32_16x16x32_bf16 v[52:55], v[32:35], v[20:23], v[28:31]
	s_waitcnt lgkmcnt(13)
	v_mfma_f32_16x16x32_bf16 v[28:31], v[36:39], v[24:27], 0
	s_waitcnt lgkmcnt(12)
	v_mfma_f32_16x16x32_bf16 v[48:51], v[40:43], v[20:23], v[28:31]
	s_waitcnt lgkmcnt(11)
	v_mfma_f32_16x16x32_bf16 v[28:31], v[44:47], v[24:27], 0
	s_waitcnt lgkmcnt(10)
	v_mfma_f32_16x16x32_bf16 v[44:47], v[164:167], v[20:23], v[28:31]
	s_waitcnt lgkmcnt(9)
	v_mfma_f32_16x16x32_bf16 v[28:31], v[168:171], v[24:27], 0
	s_waitcnt lgkmcnt(8)
	v_mfma_f32_16x16x32_bf16 v[40:43], v[172:175], v[20:23], v[28:31]
	s_waitcnt lgkmcnt(7)
	v_mfma_f32_16x16x32_bf16 v[28:31], v[176:179], v[24:27], 0
	s_waitcnt lgkmcnt(6)
	v_mfma_f32_16x16x32_bf16 v[36:39], v[180:183], v[20:23], v[28:31]
	s_waitcnt lgkmcnt(5)
	v_mfma_f32_16x16x32_bf16 v[28:31], v[200:203], v[24:27], 0
	s_waitcnt lgkmcnt(4)
	v_mfma_f32_16x16x32_bf16 v[32:35], v[204:207], v[20:23], v[28:31]
	s_waitcnt lgkmcnt(3)
	v_mfma_f32_16x16x32_bf16 v[28:31], v[208:211], v[24:27], 0
	s_waitcnt lgkmcnt(1)
	v_mfma_f32_16x16x32_bf16 v[24:27], v[216:219], v[24:27], 0
	v_mfma_f32_16x16x32_bf16 v[28:31], v[212:215], v[20:23], v[28:31]
	s_waitcnt lgkmcnt(0)
	v_mfma_f32_16x16x32_bf16 v[20:23], v[220:223], v[20:23], v[24:27]
	s_setprio 0
	s_lshl_b32 s26, s90, 6
	s_or_b32 s39, s26, 16
	s_sub_i32 s67, s39, s70
	s_add_i32 s67, s67, s91
	s_cmp_eq_u32 s67, s38
	s_cbranch_scc1 .LBB0_718
	s_sub_i32 s39, s0, s70
	s_add_i32 s39, s39, s91
	s_mul_i32 s39, s39, 31
	v_sub_u32_e32 v0, s39, v61
	s_mulk_i32 s90, 0x744
	v_add_u32_e32 v24, 0xe8, v0
	s_add_i32 s38, s90, 0
	v_add_u32_e32 v25, v24, v88
	v_add_u32_e32 v26, v24, v121
	v_add_u32_e32 v27, v24, v122
	v_add_u32_e32 v129, v24, v123
	v_add_u32_e32 v130, v24, v120
	v_add_u32_e32 v131, v24, v124
	v_add_u32_e32 v132, v24, v125
	v_add_u32_e32 v24, v24, v126
	s_add_i32 s38, s38, 0x22400
	v_cndmask_b32_e64 v129, 0, v129, s[48:49]
	v_cndmask_b32_e64 v130, 0, v130, s[40:41]
	v_cndmask_b32_e64 v131, 0, v131, s[50:51]
	v_cndmask_b32_e64 v132, 0, v132, s[52:53]
	v_cndmask_b32_e64 v24, 0, v24, s[54:55]
	v_cndmask_b32_e64 v25, 0, v25, s[42:43]
	v_cndmask_b32_e64 v26, 0, v26, s[44:45]
	v_cndmask_b32_e64 v27, 0, v27, s[46:47]
	v_lshl_add_u32 v129, v129, 2, s38
	v_lshl_add_u32 v130, v130, 2, s38
	v_lshl_add_u32 v131, v131, 2, s38
	v_lshl_add_u32 v132, v132, 2, s38
	v_lshl_add_u32 v24, v24, 2, s38
	v_lshl_add_u32 v25, v25, 2, s38
	v_lshl_add_u32 v26, v26, 2, s38
	v_lshl_add_u32 v27, v27, 2, s38
	ds_read_b32 v136, v24
	ds_read_b32 v135, v132
	ds_read_b32 v134, v131
	ds_read_b32 v133, v130
	ds_read_b32 v132, v129
	ds_read_b32 v131, v27
	ds_read_b32 v130, v26
	ds_read_b32 v129, v25
	v_add_u32_e32 v24, 0x107, v0
	v_add_u32_e32 v25, v24, v88
	v_add_u32_e32 v26, v24, v121
	v_add_u32_e32 v27, v24, v122
	v_add_u32_e32 v137, v24, v123
	v_add_u32_e32 v138, v24, v120
	v_add_u32_e32 v139, v24, v124
	v_add_u32_e32 v140, v24, v125
	v_add_u32_e32 v24, v24, v126
	v_cndmask_b32_e64 v137, 0, v137, s[48:49]
	v_cndmask_b32_e64 v138, 0, v138, s[40:41]
	v_cndmask_b32_e64 v139, 0, v139, s[50:51]
	v_cndmask_b32_e64 v140, 0, v140, s[52:53]
	v_cndmask_b32_e64 v24, 0, v24, s[54:55]
	v_cndmask_b32_e64 v25, 0, v25, s[42:43]
	v_cndmask_b32_e64 v26, 0, v26, s[44:45]
	v_cndmask_b32_e64 v27, 0, v27, s[46:47]
	v_lshl_add_u32 v137, v137, 2, s38
	v_lshl_add_u32 v138, v138, 2, s38
	v_lshl_add_u32 v139, v139, 2, s38
	v_lshl_add_u32 v140, v140, 2, s38
	v_lshl_add_u32 v24, v24, 2, s38
	s_waitcnt lgkmcnt(0)
	v_lshl_add_u32 v25, v25, 2, s38
	v_lshl_add_u32 v26, v26, 2, s38
	v_lshl_add_u32 v27, v27, 2, s38
	ds_read_b32 v144, v24
	ds_read_b32 v143, v140
	ds_read_b32 v142, v139
	ds_read_b32 v141, v138
	ds_read_b32 v140, v137
	ds_read_b32 v139, v27
	ds_read_b32 v138, v26
	ds_read_b32 v137, v25
	v_add_u32_e32 v24, 0x126, v0
	v_add_u32_e32 v25, v24, v88
	v_add_u32_e32 v26, v24, v121
	v_add_u32_e32 v27, v24, v122
	v_add_u32_e32 v145, v24, v123
	v_add_u32_e32 v146, v24, v120
	v_add_u32_e32 v147, v24, v124
	v_add_u32_e32 v148, v24, v125
	v_add_u32_e32 v24, v24, v126
	v_cndmask_b32_e64 v145, 0, v145, s[48:49]
	v_cndmask_b32_e64 v146, 0, v146, s[40:41]
	v_cndmask_b32_e64 v147, 0, v147, s[50:51]
	v_cndmask_b32_e64 v148, 0, v148, s[52:53]
	v_cndmask_b32_e64 v24, 0, v24, s[54:55]
	v_cndmask_b32_e64 v25, 0, v25, s[42:43]
	v_cndmask_b32_e64 v26, 0, v26, s[44:45]
	v_cndmask_b32_e64 v27, 0, v27, s[46:47]
	v_lshl_add_u32 v145, v145, 2, s38
	v_lshl_add_u32 v146, v146, 2, s38
	v_lshl_add_u32 v147, v147, 2, s38
	v_lshl_add_u32 v148, v148, 2, s38
	v_lshl_add_u32 v24, v24, 2, s38
	s_waitcnt lgkmcnt(0)
	v_lshl_add_u32 v25, v25, 2, s38
	v_lshl_add_u32 v26, v26, 2, s38
	v_lshl_add_u32 v27, v27, 2, s38
	ds_read_b32 v155, v24
	ds_read_b32 v154, v148
	ds_read_b32 v152, v147
	ds_read_b32 v149, v146
	ds_read_b32 v148, v145
	ds_read_b32 v147, v27
	ds_read_b32 v146, v26
	ds_read_b32 v145, v25
	v_add_u32_e32 v0, 0x145, v0
	v_add_u32_e32 v24, v0, v88
	v_add_u32_e32 v25, v0, v121
	v_add_u32_e32 v26, v0, v122
	v_add_u32_e32 v27, v0, v123
	v_add_u32_e32 v156, v0, v120
	v_add_u32_e32 v157, v0, v124
	v_add_u32_e32 v158, v0, v125
	v_add_u32_e32 v0, v0, v126
	v_cndmask_b32_e64 v156, 0, v156, s[40:41]
	v_cndmask_b32_e64 v157, 0, v157, s[50:51]
	v_cndmask_b32_e64 v158, 0, v158, s[52:53]
	v_cndmask_b32_e64 v0, 0, v0, s[54:55]
	v_cndmask_b32_e64 v24, 0, v24, s[42:43]
	v_cndmask_b32_e64 v25, 0, v25, s[44:45]
	v_cndmask_b32_e64 v26, 0, v26, s[46:47]
	v_cndmask_b32_e64 v27, 0, v27, s[48:49]
	v_lshl_add_u32 v156, v156, 2, s38
	v_lshl_add_u32 v157, v157, 2, s38
	v_lshl_add_u32 v158, v158, 2, s38
	v_lshl_add_u32 v0, v0, 2, s38
	s_waitcnt lgkmcnt(0)
	v_lshl_add_u32 v24, v24, 2, s38
	v_lshl_add_u32 v25, v25, 2, s38
	v_lshl_add_u32 v26, v26, 2, s38
	v_lshl_add_u32 v27, v27, 2, s38
	ds_read_b32 v163, v0
	ds_read_b32 v162, v158
	ds_read_b32 v161, v157
	ds_read_b32 v160, v156
	ds_read_b32 v159, v27
	ds_read_b32 v158, v26
	ds_read_b32 v157, v25
	ds_read_b32 v156, v24
	s_mov_b32 s38, s67
	s_waitcnt lgkmcnt(0)
